# ret_out output epilogue: hoist 8 gate loads + gn weights to epilogue top, counted vmcnt(7) waits (stores out of the wait chain)
# speedup vs baseline: 1.0020x; 1.0007x over previous
; #define LAS __attribute__((address_space(3)))
; #define LDS_WAIT() asm volatile("s_waitcnt lgkmcnt(0)" ::: "memory")
; __device__ __forceinline__ unsigned cvt_pk_bf16(float lo, float hi) { f32x2 v = {lo, hi}; bf16v2_t r = __builtin_convertvector(v, bf16v2_t); return __builtin_bit_cast(unsigned, r); }
; __device__ __forceinline__ void phase_ret_out(const Frame& F, const Args& a, int l) {
;     ...
;         LDS_WAIT(); __syncthreads();
;         { const f32x2 ot = SX[((dj ^ 1) * 4 + qi) * 32 + li]; s1 += ot.x; s2 += ot.y; }
;         const float mu = s1 * (1.0f / 256.0f); const float var = fmaxf(s2 * (1.0f / 256.0f) - mu * mu, 0.f); const float rstd = 1.0f / sqrtf(var + 1e-5f);
; #pragma unroll
;         for (int dt = 0; dt < 4; ++dt)
; #pragma unroll
;             for (int q4 = 0; q4 < 4; ++q4) { v2u pw; pw.x = cvt_pk_bf16((o[dt][4 * q4] - mu) * rstd, (o[dt][4 * q4 + 1] - mu) * rstd); pw.y = cvt_pk_bf16((o[dt][4 * q4 + 2] - mu) * rstd, (o[dt][4 * q4 + 3] - mu) * rstd);
;                 *(LAS v2u*)(stg + li * PLD + (32 * dt + 8 * q4 + 4 * hh) * 2) = pw; }
;     ...
;             const int idx = lane + 64 * j, q = idx >> 4, cv = idx & 15, col = h * 256 + 128 * dj + 8 * cv;
;             const v4u ov = *(const LAS v4u*)(stg + q * PLD + cv * 16);
;             const size_t tok = tok0 + 32 * qi + q;
;             const v4u gv = *(const v4u*)(RG + tok * 1024 + col);
;             const f32x4 r0 = *(const f32x4*)(rn + col), r1 = *(const f32x4*)(rn + col + 4);
.LBB0_1205:
	s_or_b64 exec, exec, s[6:7]
	v_lshl_add_u32 v172, s23, 8, v117
	v_ashrrev_i32_e32 v173, 31, v172
	v_lshlrev_b64 v[174:175], 1, v[172:173]
	v_lshl_add_u64 v[178:179], v[172:173], 2, s[18:19]
	v_lshl_add_u64 v[176:177], s[12:13], 0, v[174:175]
	global_load_dwordx4 v[164:167], v[178:179], off
	global_load_dwordx4 v[168:171], v[178:179], off offset:16
	v_mov_b32_e32 v181, s25
	v_or_b32_e32 v180, s24, v110
	v_lshlrev_b64 v[180:181], 11, v[180:181]
	v_lshl_add_u64 v[180:181], v[176:177], 0, v[180:181]
	global_load_dwordx4 v[132:135], v[180:181], off
	v_mov_b32_e32 v183, s25
	v_or_b32_e32 v182, s24, v112
	v_lshlrev_b64 v[182:183], 11, v[182:183]
	v_lshl_add_u64 v[182:183], v[176:177], 0, v[182:183]
	global_load_dwordx4 v[136:139], v[182:183], off
	v_mov_b32_e32 v181, s25
	v_or_b32_e32 v180, s24, v114
	v_lshlrev_b64 v[180:181], 11, v[180:181]
	v_lshl_add_u64 v[180:181], v[176:177], 0, v[180:181]
	global_load_dwordx4 v[140:143], v[180:181], off
	v_mov_b32_e32 v183, s25
	v_or_b32_e32 v182, s24, v116
	v_lshlrev_b64 v[182:183], 11, v[182:183]
	v_lshl_add_u64 v[182:183], v[176:177], 0, v[182:183]
	global_load_dwordx4 v[144:147], v[182:183], off
	v_mov_b32_e32 v181, s25
	v_or_b32_e32 v180, s24, v118
	v_lshlrev_b64 v[180:181], 11, v[180:181]
	v_lshl_add_u64 v[180:181], v[176:177], 0, v[180:181]
	global_load_dwordx4 v[148:151], v[180:181], off
	v_mov_b32_e32 v183, s25
	v_or_b32_e32 v182, s24, v120
	v_lshlrev_b64 v[182:183], 11, v[182:183]
	v_lshl_add_u64 v[182:183], v[176:177], 0, v[182:183]
	global_load_dwordx4 v[152:155], v[182:183], off
	v_mov_b32_e32 v181, s25
	v_or_b32_e32 v180, s24, v122
	v_lshlrev_b64 v[180:181], 11, v[180:181]
	v_lshl_add_u64 v[180:181], v[176:177], 0, v[180:181]
	global_load_dwordx4 v[156:159], v[180:181], off
	v_mov_b32_e32 v183, s25
	v_or_b32_e32 v182, s24, v124
	v_lshlrev_b64 v[182:183], 11, v[182:183]
	v_lshl_add_u64 v[182:183], v[176:177], 0, v[182:183]
	global_load_dwordx4 v[160:163], v[182:183], off
	s_waitcnt lgkmcnt(0)
	s_waitcnt lgkmcnt(0)
	s_barrier
	ds_read_b64 v[66:67], v115 offset:34816
	s_mov_b32 s6, 0x3b800000
	s_add_i32 s29, s29, s28
	s_cmpk_lt_i32 s29, 0x500
	s_waitcnt lgkmcnt(0)
	v_pk_add_f32 v[64:65], v[64:65], v[66:67]
	s_nop 0
	v_pk_mul_f32 v[64:65], v[64:65], s[6:7] op_sel_hi:[1,0]
	s_nop 0
	v_fma_f32 v66, -v64, v64, v65
	v_max_f32_e32 v66, 0, v66
	v_add_f32_e32 v66, 0x3727c5ac, v66
	v_mul_f32_e32 v67, 0x4f800000, v66
	v_cmp_gt_f32_e32 vcc, s86, v66
	v_pk_add_f32 v[0:1], v[0:1], v[64:65] op_sel_hi:[1,0] neg_lo:[0,1] neg_hi:[0,1]
	v_pk_add_f32 v[2:3], v[2:3], v[64:65] op_sel_hi:[1,0] neg_lo:[0,1] neg_hi:[0,1]
	v_cndmask_b32_e32 v66, v66, v67, vcc
	v_sqrt_f32_e32 v67, v66
	s_nop 0
	v_add_u32_e32 v68, -1, v67
	v_fma_f32 v70, -v68, v67, v66
	v_add_u32_e32 v69, 1, v67
	v_cmp_ge_f32_e64 s[6:7], 0, v70
	s_nop 1
	v_cndmask_b32_e64 v68, v67, v68, s[6:7]
	v_fma_f32 v67, -v69, v67, v66
	v_cmp_lt_f32_e64 s[6:7], 0, v67
	s_nop 1
	v_cndmask_b32_e64 v67, v68, v69, s[6:7]
	v_mul_f32_e32 v68, 0x37800000, v67
	v_cndmask_b32_e32 v67, v67, v68, vcc
	v_cmp_class_f32_e32 vcc, v66, v204
	s_nop 1
	v_cndmask_b32_e32 v66, v67, v66, vcc
	v_div_scale_f32 v67, s[6:7], v66, v66, 1.0
	v_rcp_f32_e32 v68, v67
	s_nop 0
	v_fma_f32 v69, -v67, v68, 1.0
	v_fmac_f32_e32 v68, v69, v68
	v_div_scale_f32 v69, vcc, 1.0, v66, 1.0
	v_mul_f32_e32 v70, v69, v68
	v_fma_f32 v71, -v67, v70, v69
	v_fmac_f32_e32 v70, v71, v68
	v_fma_f32 v67, -v67, v70, v69
	v_div_fmas_f32 v67, v67, v68, v70
	v_div_fixup_f32 v66, v67, v66, 1.0
	v_pk_mul_f32 v[0:1], v[0:1], v[66:67] op_sel_hi:[1,0]
	v_pk_mul_f32 v[2:3], v[2:3], v[66:67] op_sel_hi:[1,0]
	v_cvt_pk_bf16_f32 v0, v0, v1
	v_cvt_pk_bf16_f32 v1, v2, v3
	v_pk_add_f32 v[2:3], v[4:5], v[64:65] op_sel_hi:[1,0] neg_lo:[0,1] neg_hi:[0,1]
	v_pk_add_f32 v[4:5], v[6:7], v[64:65] op_sel_hi:[1,0] neg_lo:[0,1] neg_hi:[0,1]
	v_pk_mul_f32 v[2:3], v[2:3], v[66:67] op_sel_hi:[1,0]
	v_pk_mul_f32 v[4:5], v[4:5], v[66:67] op_sel_hi:[1,0]
	v_cvt_pk_bf16_f32 v2, v2, v3
	v_cvt_pk_bf16_f32 v3, v4, v5
	v_add_u32_e32 v6, 0xa000, v125
	ds_write2_b64 v6, v[0:1], v[2:3] offset1:2
	v_pk_add_f32 v[0:1], v[8:9], v[64:65] op_sel_hi:[1,0] neg_lo:[0,1] neg_hi:[0,1]
	v_pk_add_f32 v[2:3], v[10:11], v[64:65] op_sel_hi:[1,0] neg_lo:[0,1] neg_hi:[0,1]
	v_pk_mul_f32 v[0:1], v[0:1], v[66:67] op_sel_hi:[1,0]
	v_pk_mul_f32 v[2:3], v[2:3], v[66:67] op_sel_hi:[1,0]
	v_cvt_pk_bf16_f32 v0, v0, v1
	v_cvt_pk_bf16_f32 v1, v2, v3
	v_pk_add_f32 v[2:3], v[12:13], v[64:65] op_sel_hi:[1,0] neg_lo:[0,1] neg_hi:[0,1]
	v_pk_add_f32 v[4:5], v[14:15], v[64:65] op_sel_hi:[1,0] neg_lo:[0,1] neg_hi:[0,1]
	v_pk_mul_f32 v[2:3], v[2:3], v[66:67] op_sel_hi:[1,0]
	v_pk_mul_f32 v[4:5], v[4:5], v[66:67] op_sel_hi:[1,0]
	v_cvt_pk_bf16_f32 v2, v2, v3
	v_cvt_pk_bf16_f32 v3, v4, v5
	ds_write2_b64 v6, v[0:1], v[2:3] offset0:4 offset1:6
	v_pk_add_f32 v[0:1], v[16:17], v[64:65] op_sel_hi:[1,0] neg_lo:[0,1] neg_hi:[0,1]
	v_pk_add_f32 v[2:3], v[18:19], v[64:65] op_sel_hi:[1,0] neg_lo:[0,1] neg_hi:[0,1]
	v_pk_mul_f32 v[0:1], v[0:1], v[66:67] op_sel_hi:[1,0]
	v_pk_mul_f32 v[2:3], v[2:3], v[66:67] op_sel_hi:[1,0]
	v_cvt_pk_bf16_f32 v0, v0, v1
	v_cvt_pk_bf16_f32 v1, v2, v3
	v_pk_add_f32 v[2:3], v[20:21], v[64:65] op_sel_hi:[1,0] neg_lo:[0,1] neg_hi:[0,1]
	v_pk_add_f32 v[4:5], v[22:23], v[64:65] op_sel_hi:[1,0] neg_lo:[0,1] neg_hi:[0,1]
	v_pk_mul_f32 v[2:3], v[2:3], v[66:67] op_sel_hi:[1,0]
	v_pk_mul_f32 v[4:5], v[4:5], v[66:67] op_sel_hi:[1,0]
	v_cvt_pk_bf16_f32 v2, v2, v3
	v_cvt_pk_bf16_f32 v3, v4, v5
	ds_write2_b64 v6, v[0:1], v[2:3] offset0:8 offset1:10
	v_pk_add_f32 v[0:1], v[24:25], v[64:65] op_sel_hi:[1,0] neg_lo:[0,1] neg_hi:[0,1]
	v_pk_add_f32 v[2:3], v[26:27], v[64:65] op_sel_hi:[1,0] neg_lo:[0,1] neg_hi:[0,1]
; #define LAS __attribute__((address_space(3)))
; #define LDS_WAIT() asm volatile("s_waitcnt lgkmcnt(0)" ::: "memory")
; __device__ __forceinline__ unsigned cvt_pk_bf16(float lo, float hi) { f32x2 v = {lo, hi}; bf16v2_t r = __builtin_convertvector(v, bf16v2_t); return __builtin_bit_cast(unsigned, r); }
; __device__ __forceinline__ unsigned pk2(float lo, float hi) { return cvt_pk_bf16(lo, hi); }
; __device__ __forceinline__ float fsigmoid(float x) { return __builtin_amdgcn_rcpf(1.0f + fexp(-x)); }
; __device__ __forceinline__ void phase_ret_out(const Frame& F, const Args& a, int l) {
;     ...
;             for (int q4 = 0; q4 < 4; ++q4) { v2u pw; pw.x = cvt_pk_bf16((o[dt][4 * q4] - mu) * rstd, (o[dt][4 * q4 + 1] - mu) * rstd); pw.y = cvt_pk_bf16((o[dt][4 * q4 + 2] - mu) * rstd, (o[dt][4 * q4 + 3] - mu) * rstd);
;                 *(LAS v2u*)(stg + li * PLD + (32 * dt + 8 * q4 + 4 * hh) * 2) = pw; }
;         LDS_WAIT(); asm volatile("" ::: "memory");
; #pragma unroll
;         for (int j = 0; j < 8; ++j) {
;             const int idx = lane + 64 * j, q = idx >> 4, cv = idx & 15, col = h * 256 + 128 * dj + 8 * cv;
;             const v4u ov = *(const LAS v4u*)(stg + q * PLD + cv * 16);
;             const size_t tok = tok0 + 32 * qi + q;
;             const v4u gv = *(const v4u*)(RG + tok * 1024 + col);
;             const f32x4 r0 = *(const f32x4*)(rn + col), r1 = *(const f32x4*)(rn + col + 4);
;             const float rr[8] = {r0.x, r0.y, r0.z, r0.w, r1.x, r1.y, r1.z, r1.w};
;             v4u wv;
; #pragma unroll
;             for (int q2 = 0; q2 < 4; ++q2) { const float ga = bf_lo(gv[q2]), gb = bf_hi(gv[q2]);
;                 wv[q2] = pk2(ga * fsigmoid(ga) * bf_lo(ov[q2]) * rr[2 * q2], gb * fsigmoid(gb) * bf_hi(ov[q2]) * rr[2 * q2 + 1]); }
;             *(v4u*)(YB + tok * 1024 + col) = wv;
	v_pk_mul_f32 v[0:1], v[0:1], v[66:67] op_sel_hi:[1,0]
	v_pk_mul_f32 v[2:3], v[2:3], v[66:67] op_sel_hi:[1,0]
	v_cvt_pk_bf16_f32 v0, v0, v1
	v_cvt_pk_bf16_f32 v1, v2, v3
	v_pk_add_f32 v[2:3], v[28:29], v[64:65] op_sel_hi:[1,0] neg_lo:[0,1] neg_hi:[0,1]
	v_pk_add_f32 v[4:5], v[30:31], v[64:65] op_sel_hi:[1,0] neg_lo:[0,1] neg_hi:[0,1]
	v_pk_mul_f32 v[2:3], v[2:3], v[66:67] op_sel_hi:[1,0]
	v_pk_mul_f32 v[4:5], v[4:5], v[66:67] op_sel_hi:[1,0]
	v_cvt_pk_bf16_f32 v2, v2, v3
	v_cvt_pk_bf16_f32 v3, v4, v5
	ds_write2_b64 v6, v[0:1], v[2:3] offset0:12 offset1:14
	v_pk_add_f32 v[0:1], v[32:33], v[64:65] op_sel_hi:[1,0] neg_lo:[0,1] neg_hi:[0,1]
	v_pk_add_f32 v[2:3], v[34:35], v[64:65] op_sel_hi:[1,0] neg_lo:[0,1] neg_hi:[0,1]
	v_pk_mul_f32 v[0:1], v[0:1], v[66:67] op_sel_hi:[1,0]
	v_pk_mul_f32 v[2:3], v[2:3], v[66:67] op_sel_hi:[1,0]
	v_cvt_pk_bf16_f32 v0, v0, v1
	v_cvt_pk_bf16_f32 v1, v2, v3
	v_pk_add_f32 v[2:3], v[36:37], v[64:65] op_sel_hi:[1,0] neg_lo:[0,1] neg_hi:[0,1]
	v_pk_add_f32 v[4:5], v[38:39], v[64:65] op_sel_hi:[1,0] neg_lo:[0,1] neg_hi:[0,1]
	v_pk_mul_f32 v[2:3], v[2:3], v[66:67] op_sel_hi:[1,0]
	v_pk_mul_f32 v[4:5], v[4:5], v[66:67] op_sel_hi:[1,0]
	v_cvt_pk_bf16_f32 v2, v2, v3
	v_cvt_pk_bf16_f32 v3, v4, v5
	ds_write2_b64 v6, v[0:1], v[2:3] offset0:16 offset1:18
	v_pk_add_f32 v[0:1], v[40:41], v[64:65] op_sel_hi:[1,0] neg_lo:[0,1] neg_hi:[0,1]
	v_pk_add_f32 v[2:3], v[42:43], v[64:65] op_sel_hi:[1,0] neg_lo:[0,1] neg_hi:[0,1]
	v_pk_mul_f32 v[0:1], v[0:1], v[66:67] op_sel_hi:[1,0]
	v_pk_mul_f32 v[2:3], v[2:3], v[66:67] op_sel_hi:[1,0]
	v_cvt_pk_bf16_f32 v0, v0, v1
	v_cvt_pk_bf16_f32 v1, v2, v3
	v_pk_add_f32 v[2:3], v[44:45], v[64:65] op_sel_hi:[1,0] neg_lo:[0,1] neg_hi:[0,1]
	v_pk_add_f32 v[4:5], v[46:47], v[64:65] op_sel_hi:[1,0] neg_lo:[0,1] neg_hi:[0,1]
	v_pk_mul_f32 v[2:3], v[2:3], v[66:67] op_sel_hi:[1,0]
	v_pk_mul_f32 v[4:5], v[4:5], v[66:67] op_sel_hi:[1,0]
	v_cvt_pk_bf16_f32 v2, v2, v3
	v_cvt_pk_bf16_f32 v3, v4, v5
	ds_write2_b64 v6, v[0:1], v[2:3] offset0:20 offset1:22
	v_pk_add_f32 v[0:1], v[48:49], v[64:65] op_sel_hi:[1,0] neg_lo:[0,1] neg_hi:[0,1]
	v_pk_add_f32 v[2:3], v[50:51], v[64:65] op_sel_hi:[1,0] neg_lo:[0,1] neg_hi:[0,1]
	v_pk_mul_f32 v[0:1], v[0:1], v[66:67] op_sel_hi:[1,0]
	v_pk_mul_f32 v[2:3], v[2:3], v[66:67] op_sel_hi:[1,0]
	v_cvt_pk_bf16_f32 v0, v0, v1
	v_cvt_pk_bf16_f32 v1, v2, v3
	v_pk_add_f32 v[2:3], v[52:53], v[64:65] op_sel_hi:[1,0] neg_lo:[0,1] neg_hi:[0,1]
	v_pk_add_f32 v[4:5], v[54:55], v[64:65] op_sel_hi:[1,0] neg_lo:[0,1] neg_hi:[0,1]
	v_pk_mul_f32 v[2:3], v[2:3], v[66:67] op_sel_hi:[1,0]
	v_pk_mul_f32 v[4:5], v[4:5], v[66:67] op_sel_hi:[1,0]
	v_cvt_pk_bf16_f32 v2, v2, v3
	v_cvt_pk_bf16_f32 v3, v4, v5
	ds_write2_b64 v6, v[0:1], v[2:3] offset0:24 offset1:26
	v_pk_add_f32 v[0:1], v[56:57], v[64:65] op_sel_hi:[1,0] neg_lo:[0,1] neg_hi:[0,1]
	v_pk_add_f32 v[2:3], v[58:59], v[64:65] op_sel_hi:[1,0] neg_lo:[0,1] neg_hi:[0,1]
	v_pk_mul_f32 v[0:1], v[0:1], v[66:67] op_sel_hi:[1,0]
	v_pk_mul_f32 v[2:3], v[2:3], v[66:67] op_sel_hi:[1,0]
	v_cvt_pk_bf16_f32 v0, v0, v1
	v_cvt_pk_bf16_f32 v1, v2, v3
	v_pk_add_f32 v[2:3], v[60:61], v[64:65] op_sel_hi:[1,0] neg_lo:[0,1] neg_hi:[0,1]
	v_pk_add_f32 v[4:5], v[62:63], v[64:65] op_sel_hi:[1,0] neg_lo:[0,1] neg_hi:[0,1]
	v_pk_mul_f32 v[2:3], v[2:3], v[66:67] op_sel_hi:[1,0]
	v_pk_mul_f32 v[4:5], v[4:5], v[66:67] op_sel_hi:[1,0]
	v_cvt_pk_bf16_f32 v2, v2, v3
	v_cvt_pk_bf16_f32 v3, v4, v5
	ds_write2_b64 v6, v[0:1], v[2:3] offset0:28 offset1:30
	v_lshl_add_u32 v0, s23, 8, v117
	v_ashrrev_i32_e32 v1, 31, v0
	v_lshlrev_b64 v[2:3], 1, v[0:1]
	v_mov_b32_e32 v5, s25
	v_or_b32_e32 v4, s24, v110
	s_waitcnt lgkmcnt(0)
	v_lshl_add_u64 v[8:9], s[12:13], 0, v[2:3]
	v_lshlrev_b64 v[26:27], 11, v[4:5]
	v_lshl_add_u64 v[4:5], v[8:9], 0, v[26:27]
	s_nop 1
	s_waitcnt vmcnt(7)
	v_mov_b32_e32 v10, v132
	v_mov_b32_e32 v11, v133
	v_mov_b32_e32 v12, v134
	v_mov_b32_e32 v13, v135
	v_lshl_add_u64 v[6:7], v[0:1], 2, s[18:19]
	v_mov_b32_e32 v14, v164
	v_mov_b32_e32 v15, v165
	v_mov_b32_e32 v16, v166
	v_mov_b32_e32 v17, v167
	v_mov_b32_e32 v18, v168
	v_mov_b32_e32 v19, v169
	v_mov_b32_e32 v20, v170
	v_mov_b32_e32 v21, v171
	ds_read_b128 v[22:25], v129 offset:40960
	s_nop 0
	v_lshlrev_b32_e32 v0, 16, v10
	v_and_b32_e32 v1, 0xffff0000, v10
	v_mul_f32_e32 v4, 0xbfb8aa3b, v0
	v_exp_f32_e32 v4, v4
	v_mul_f32_e32 v5, 0xbfb8aa3b, v1
	v_exp_f32_e32 v5, v5
	v_lshlrev_b32_e32 v30, 16, v11
	v_add_f32_e32 v4, 1.0, v4
	v_rcp_f32_e32 v28, v4
	v_add_f32_e32 v4, 1.0, v5
	v_and_b32_e32 v31, 0xffff0000, v11
	v_mul_f32_e32 v11, 0xbfb8aa3b, v30
	v_rcp_f32_e32 v29, v4
	v_exp_f32_e32 v32, v11
	v_mul_f32_e32 v11, 0xbfb8aa3b, v31
	v_exp_f32_e32 v33, v11
	v_lshl_add_u64 v[4:5], s[14:15], 0, v[2:3]
	v_pk_mul_f32 v[28:29], v[28:29], v[0:1]
	ds_read_b128 v[0:3], v129 offset:42048
	s_waitcnt lgkmcnt(1)
; #define LAS __attribute__((address_space(3)))
; __device__ __forceinline__ unsigned pk2(float lo, float hi) { return cvt_pk_bf16(lo, hi); }
; __device__ __forceinline__ float fsigmoid(float x) { return __builtin_amdgcn_rcpf(1.0f + fexp(-x)); }
; __device__ __forceinline__ void phase_ret_out(const Frame& F, const Args& a, int l) {
;     ...
;         for (int j = 0; j < 8; ++j) {
;             const int idx = lane + 64 * j, q = idx >> 4, cv = idx & 15, col = h * 256 + 128 * dj + 8 * cv;
;             const v4u ov = *(const LAS v4u*)(stg + q * PLD + cv * 16);
;             const size_t tok = tok0 + 32 * qi + q;
;             const v4u gv = *(const v4u*)(RG + tok * 1024 + col);
;             const f32x4 r0 = *(const f32x4*)(rn + col), r1 = *(const f32x4*)(rn + col + 4);
;             const float rr[8] = {r0.x, r0.y, r0.z, r0.w, r1.x, r1.y, r1.z, r1.w};
;             v4u wv;
; #pragma unroll
;             for (int q2 = 0; q2 < 4; ++q2) { const float ga = bf_lo(gv[q2]), gb = bf_hi(gv[q2]);
;                 wv[q2] = pk2(ga * fsigmoid(ga) * bf_lo(ov[q2]) * rr[2 * q2], gb * fsigmoid(gb) * bf_hi(ov[q2]) * rr[2 * q2 + 1]); }
;             *(v4u*)(YB + tok * 1024 + col) = wv;
	v_lshlrev_b32_e32 v10, 16, v22
	v_and_b32_e32 v11, 0xffff0000, v22
	v_add_f32_e32 v22, 1.0, v32
	v_rcp_f32_e32 v32, v22
	v_add_f32_e32 v22, 1.0, v33
	v_rcp_f32_e32 v33, v22
	v_pk_mul_f32 v[10:11], v[28:29], v[10:11]
	v_lshlrev_b32_e32 v22, 16, v23
	s_nop 0
	v_pk_mul_f32 v[10:11], v[14:15], v[10:11]
	v_pk_mul_f32 v[14:15], v[32:33], v[30:31]
	v_and_b32_e32 v23, 0xffff0000, v23
	v_lshlrev_b32_e32 v28, 16, v12
	v_pk_mul_f32 v[14:15], v[14:15], v[22:23]
	v_cvt_pk_bf16_f32 v10, v10, v11
	v_and_b32_e32 v29, 0xffff0000, v12
	v_mul_f32_e32 v11, 0xbfb8aa3b, v28
	v_pk_mul_f32 v[14:15], v[16:17], v[14:15]
	v_lshlrev_b32_e32 v16, 16, v13
	v_exp_f32_e32 v11, v11
	v_mul_f32_e32 v12, 0xbfb8aa3b, v29
	v_and_b32_e32 v17, 0xffff0000, v13
	v_mul_f32_e32 v13, 0xbfb8aa3b, v16
	v_exp_f32_e32 v12, v12
	v_exp_f32_e32 v22, v13
	v_mul_f32_e32 v13, 0xbfb8aa3b, v17
	v_exp_f32_e32 v23, v13
	v_add_f32_e32 v11, 1.0, v11
	v_rcp_f32_e32 v30, v11
	v_add_f32_e32 v11, 1.0, v12
	v_rcp_f32_e32 v31, v11
	v_add_f32_e32 v22, 1.0, v22
	v_add_f32_e32 v23, 1.0, v23
	v_rcp_f32_e32 v22, v22
	v_rcp_f32_e32 v23, v23
	v_cvt_pk_bf16_f32 v11, v14, v15
	v_pk_mul_f32 v[14:15], v[30:31], v[28:29]
	v_lshlrev_b32_e32 v12, 16, v24
	v_and_b32_e32 v13, 0xffff0000, v24
	v_pk_mul_f32 v[12:13], v[14:15], v[12:13]
	v_pk_mul_f32 v[14:15], v[22:23], v[16:17]
	v_lshlrev_b32_e32 v16, 16, v25
	v_and_b32_e32 v17, 0xffff0000, v25
	v_pk_mul_f32 v[14:15], v[14:15], v[16:17]
	s_nop 0
	v_pk_mul_f32 v[12:13], v[18:19], v[12:13]
	v_pk_mul_f32 v[14:15], v[20:21], v[14:15]
	v_cvt_pk_bf16_f32 v12, v12, v13
	v_cvt_pk_bf16_f32 v13, v14, v15
	v_lshl_add_u64 v[14:15], v[4:5], 0, v[26:27]
	global_store_dwordx4 v[14:15], v[10:13], off
	s_nop 1
	v_mov_b32_e32 v11, s25
	v_or_b32_e32 v10, s24, v112
	v_lshlrev_b64 v[22:23], 11, v[10:11]
	v_lshl_add_u64 v[10:11], v[8:9], 0, v[22:23]
	s_nop 1
	s_waitcnt vmcnt(7)
	v_mov_b32_e32 v10, v136
	v_mov_b32_e32 v11, v137
	v_mov_b32_e32 v12, v138
	v_mov_b32_e32 v13, v139
	s_nop 0
	v_mov_b32_e32 v14, v164
	v_mov_b32_e32 v15, v165
	v_mov_b32_e32 v16, v166
	v_mov_b32_e32 v17, v167
	v_mov_b32_e32 v18, v168
	v_mov_b32_e32 v19, v169
	v_mov_b32_e32 v20, v170
	v_mov_b32_e32 v21, v171
	s_nop 0
	v_lshlrev_b32_e32 v24, 16, v10
	v_and_b32_e32 v25, 0xffff0000, v10
	v_mul_f32_e32 v10, 0xbfb8aa3b, v24
	v_exp_f32_e32 v10, v10
	v_mul_f32_e32 v26, 0xbfb8aa3b, v25
	v_exp_f32_e32 v27, v26
	v_add_f32_e32 v10, 1.0, v10
	v_rcp_f32_e32 v26, v10
	v_add_f32_e32 v10, 1.0, v27
	v_rcp_f32_e32 v27, v10
	s_waitcnt lgkmcnt(0)
	v_lshlrev_b32_e32 v10, 16, v0
	v_pk_mul_f32 v[24:25], v[26:27], v[24:25]
	v_lshlrev_b32_e32 v26, 16, v11
	v_and_b32_e32 v27, 0xffff0000, v11
	v_mul_f32_e32 v11, 0xbfb8aa3b, v26
	v_exp_f32_e32 v28, v11
	v_mul_f32_e32 v11, 0xbfb8aa3b, v27
	v_exp_f32_e32 v29, v11
	v_and_b32_e32 v11, 0xffff0000, v0
	v_add_f32_e32 v0, 1.0, v28
	v_rcp_f32_e32 v28, v0
	v_add_f32_e32 v0, 1.0, v29
	v_rcp_f32_e32 v29, v0
	v_pk_mul_f32 v[10:11], v[24:25], v[10:11]
	v_lshlrev_b32_e32 v24, 16, v12
	v_and_b32_e32 v25, 0xffff0000, v12
	s_nop 0
	v_pk_mul_f32 v[10:11], v[14:15], v[10:11]
	v_mul_f32_e32 v12, 0xbfb8aa3b, v24
	v_mul_f32_e32 v15, 0xbfb8aa3b, v25
	v_cvt_pk_bf16_f32 v0, v10, v11
	v_pk_mul_f32 v[10:11], v[28:29], v[26:27]
	v_lshlrev_b32_e32 v14, 16, v1
	v_exp_f32_e32 v12, v12
	v_exp_f32_e32 v27, v15
	v_and_b32_e32 v15, 0xffff0000, v1
	v_pk_mul_f32 v[10:11], v[10:11], v[14:15]
	v_lshlrev_b32_e32 v14, 16, v13
	v_and_b32_e32 v15, 0xffff0000, v13
	v_mul_f32_e32 v13, 0xbfb8aa3b, v14
	v_pk_mul_f32 v[10:11], v[16:17], v[10:11]
	v_exp_f32_e32 v16, v13
	v_mul_f32_e32 v13, 0xbfb8aa3b, v15
	v_add_f32_e32 v1, 1.0, v12
	v_exp_f32_e32 v17, v13
	v_rcp_f32_e32 v26, v1
	v_add_f32_e32 v1, 1.0, v27
	v_rcp_f32_e32 v27, v1
	v_lshlrev_b32_e32 v12, 16, v2
	v_and_b32_e32 v13, 0xffff0000, v2
	v_add_f32_e32 v2, 1.0, v16
	v_rcp_f32_e32 v16, v2
	v_add_f32_e32 v2, 1.0, v17
	v_rcp_f32_e32 v17, v2
	v_cvt_pk_bf16_f32 v1, v10, v11
	v_pk_mul_f32 v[10:11], v[26:27], v[24:25]
	s_nop 0
	v_pk_mul_f32 v[10:11], v[10:11], v[12:13]
	v_lshlrev_b32_e32 v12, 16, v3
	s_nop 0
	v_pk_mul_f32 v[10:11], v[18:19], v[10:11]
	v_and_b32_e32 v13, 0xffff0000, v3
	v_cvt_pk_bf16_f32 v2, v10, v11
	v_pk_mul_f32 v[10:11], v[16:17], v[14:15]
	s_nop 0
	v_pk_mul_f32 v[10:11], v[10:11], v[12:13]
	s_nop 0
	v_pk_mul_f32 v[10:11], v[20:21], v[10:11]
	s_nop 0
	v_cvt_pk_bf16_f32 v3, v10, v11
	v_lshl_add_u64 v[10:11], v[4:5], 0, v[22:23]
	global_store_dwordx4 v[10:11], v[0:3], off
	s_nop 1
	v_mov_b32_e32 v1, s25
	v_or_b32_e32 v0, s24, v114
	v_lshlrev_b64 v[26:27], 11, v[0:1]
	v_lshl_add_u64 v[0:1], v[8:9], 0, v[26:27]
	s_nop 1
	s_waitcnt vmcnt(7)
	v_mov_b32_e32 v10, v140
	v_mov_b32_e32 v11, v141
	v_mov_b32_e32 v12, v142
	v_mov_b32_e32 v13, v143
	v_mov_b32_e32 v14, v164
	v_mov_b32_e32 v15, v165
	v_mov_b32_e32 v16, v166
	v_mov_b32_e32 v17, v167
	v_mov_b32_e32 v18, v168
	v_mov_b32_e32 v19, v169
	v_mov_b32_e32 v20, v170
	v_mov_b32_e32 v21, v171
	ds_read_b128 v[22:25], v129 offset:43136
	s_nop 0
	v_lshlrev_b32_e32 v28, 16, v10
	v_and_b32_e32 v29, 0xffff0000, v10
	v_mul_f32_e32 v0, 0xbfb8aa3b, v28
	v_mul_f32_e32 v1, 0xbfb8aa3b, v29
	v_exp_f32_e32 v30, v0
	v_exp_f32_e32 v31, v1
	v_lshlrev_b32_e32 v32, 16, v11
	v_and_b32_e32 v33, 0xffff0000, v11
	v_add_f32_e32 v30, 1.0, v30
	v_add_f32_e32 v31, 1.0, v31
	v_rcp_f32_e32 v30, v30
	v_rcp_f32_e32 v31, v31
	v_mul_f32_e32 v11, 0xbfb8aa3b, v32
	ds_read_b128 v[0:3], v129 offset:44224
	s_waitcnt lgkmcnt(1)
; #define LAS __attribute__((address_space(3)))
; __device__ __forceinline__ unsigned pk2(float lo, float hi) { return cvt_pk_bf16(lo, hi); }
; __device__ __forceinline__ float fsigmoid(float x) { return __builtin_amdgcn_rcpf(1.0f + fexp(-x)); }
; __device__ __forceinline__ void phase_ret_out(const Frame& F, const Args& a, int l) {
;     ...
;         for (int j = 0; j < 8; ++j) {
;             const int idx = lane + 64 * j, q = idx >> 4, cv = idx & 15, col = h * 256 + 128 * dj + 8 * cv;
;             const v4u ov = *(const LAS v4u*)(stg + q * PLD + cv * 16);
;             const size_t tok = tok0 + 32 * qi + q;
;             const v4u gv = *(const v4u*)(RG + tok * 1024 + col);
;             const f32x4 r0 = *(const f32x4*)(rn + col), r1 = *(const f32x4*)(rn + col + 4);
;             const float rr[8] = {r0.x, r0.y, r0.z, r0.w, r1.x, r1.y, r1.z, r1.w};
;             v4u wv;
; #pragma unroll
;             for (int q2 = 0; q2 < 4; ++q2) { const float ga = bf_lo(gv[q2]), gb = bf_hi(gv[q2]);
;                 wv[q2] = pk2(ga * fsigmoid(ga) * bf_lo(ov[q2]) * rr[2 * q2], gb * fsigmoid(gb) * bf_hi(ov[q2]) * rr[2 * q2 + 1]); }
;             *(v4u*)(YB + tok * 1024 + col) = wv;
	v_lshlrev_b32_e32 v10, 16, v22
	v_pk_mul_f32 v[28:29], v[30:31], v[28:29]
	v_exp_f32_e32 v30, v11
	v_mul_f32_e32 v11, 0xbfb8aa3b, v33
	v_exp_f32_e32 v31, v11
	v_and_b32_e32 v11, 0xffff0000, v22
	v_add_f32_e32 v22, 1.0, v30
	v_rcp_f32_e32 v30, v22
	v_add_f32_e32 v22, 1.0, v31
	v_rcp_f32_e32 v31, v22
	v_pk_mul_f32 v[10:11], v[28:29], v[10:11]
	v_lshlrev_b32_e32 v22, 16, v23
	s_nop 0
	v_pk_mul_f32 v[10:11], v[14:15], v[10:11]
	v_pk_mul_f32 v[14:15], v[30:31], v[32:33]
	v_and_b32_e32 v23, 0xffff0000, v23
	v_lshlrev_b32_e32 v28, 16, v12
	v_pk_mul_f32 v[14:15], v[14:15], v[22:23]
	v_cvt_pk_bf16_f32 v10, v10, v11
	v_and_b32_e32 v29, 0xffff0000, v12
	v_mul_f32_e32 v11, 0xbfb8aa3b, v28
	v_pk_mul_f32 v[14:15], v[16:17], v[14:15]
	v_lshlrev_b32_e32 v16, 16, v13
	v_exp_f32_e32 v11, v11
	v_mul_f32_e32 v12, 0xbfb8aa3b, v29
	v_and_b32_e32 v17, 0xffff0000, v13
	v_mul_f32_e32 v13, 0xbfb8aa3b, v16
	v_exp_f32_e32 v12, v12
	v_exp_f32_e32 v22, v13
	v_mul_f32_e32 v13, 0xbfb8aa3b, v17
	v_exp_f32_e32 v23, v13
	v_add_f32_e32 v11, 1.0, v11
	v_rcp_f32_e32 v30, v11
	v_add_f32_e32 v11, 1.0, v12
	v_rcp_f32_e32 v31, v11
	v_add_f32_e32 v22, 1.0, v22
	v_add_f32_e32 v23, 1.0, v23
	v_rcp_f32_e32 v22, v22
	v_rcp_f32_e32 v23, v23
	v_cvt_pk_bf16_f32 v11, v14, v15
	v_pk_mul_f32 v[14:15], v[30:31], v[28:29]
	v_lshlrev_b32_e32 v12, 16, v24
	v_and_b32_e32 v13, 0xffff0000, v24
	v_pk_mul_f32 v[12:13], v[14:15], v[12:13]
	v_pk_mul_f32 v[14:15], v[22:23], v[16:17]
	v_lshlrev_b32_e32 v16, 16, v25
	v_and_b32_e32 v17, 0xffff0000, v25
	v_pk_mul_f32 v[14:15], v[14:15], v[16:17]
	s_nop 0
	v_pk_mul_f32 v[12:13], v[18:19], v[12:13]
	v_pk_mul_f32 v[14:15], v[20:21], v[14:15]
	v_cvt_pk_bf16_f32 v12, v12, v13
	v_cvt_pk_bf16_f32 v13, v14, v15
	v_lshl_add_u64 v[14:15], v[4:5], 0, v[26:27]
	global_store_dwordx4 v[14:15], v[10:13], off
	s_waitcnt lgkmcnt(0)
	v_lshlrev_b32_e32 v24, 16, v0
	v_and_b32_e32 v25, 0xffff0000, v0
	v_mov_b32_e32 v11, s25
	v_or_b32_e32 v10, s24, v116
	v_lshlrev_b64 v[22:23], 11, v[10:11]
	v_lshl_add_u64 v[10:11], v[8:9], 0, v[22:23]
	s_nop 1
	s_waitcnt vmcnt(7)
	v_mov_b32_e32 v10, v144
	v_mov_b32_e32 v11, v145
	v_mov_b32_e32 v12, v146
	v_mov_b32_e32 v13, v147
	s_nop 0
	v_mov_b32_e32 v14, v164
	v_mov_b32_e32 v15, v165
	v_mov_b32_e32 v16, v166
	v_mov_b32_e32 v17, v167
	v_mov_b32_e32 v18, v168
	v_mov_b32_e32 v19, v169
	v_mov_b32_e32 v20, v170
	v_mov_b32_e32 v21, v171
	v_lshlrev_b32_e32 v0, 16, v1
	v_and_b32_e32 v1, 0xffff0000, v1
	s_nop 0
	v_lshlrev_b32_e32 v26, 16, v10
	v_and_b32_e32 v27, 0xffff0000, v10
	v_lshlrev_b32_e32 v10, 16, v11
	v_and_b32_e32 v11, 0xffff0000, v11
	v_lshlrev_b32_e32 v28, 16, v12
	v_and_b32_e32 v29, 0xffff0000, v12
	v_mul_f32_e32 v12, 0xbfb8aa3b, v26
	v_mul_f32_e32 v30, 0xbfb8aa3b, v27
	v_mul_f32_e32 v31, 0xbfb8aa3b, v10
	v_mul_f32_e32 v32, 0xbfb8aa3b, v11
	v_mul_f32_e32 v33, 0xbfb8aa3b, v28
	v_exp_f32_e32 v12, v12
	v_exp_f32_e32 v30, v30
	v_exp_f32_e32 v31, v31
	v_exp_f32_e32 v32, v32
	v_exp_f32_e32 v33, v33
	v_add_f32_e32 v12, 1.0, v12
	v_add_f32_e32 v35, 1.0, v30
	v_add_f32_e32 v36, 1.0, v31
	v_add_f32_e32 v37, 1.0, v32
	v_add_f32_e32 v38, 1.0, v33
	v_rcp_f32_e32 v30, v12
	v_rcp_f32_e32 v31, v35
	v_rcp_f32_e32 v32, v36
	v_rcp_f32_e32 v33, v37
	v_mul_f32_e32 v34, 0xbfb8aa3b, v29
	v_pk_mul_f32 v[26:27], v[30:31], v[26:27]
	v_exp_f32_e32 v34, v34
	v_pk_mul_f32 v[10:11], v[32:33], v[10:11]
	v_pk_mul_f32 v[24:25], v[26:27], v[24:25]
	v_pk_mul_f32 v[0:1], v[10:11], v[0:1]
	s_nop 0
	v_pk_mul_f32 v[10:11], v[14:15], v[24:25]
	v_pk_mul_f32 v[14:15], v[16:17], v[0:1]
	v_add_f32_e32 v39, 1.0, v34
	v_cvt_pk_bf16_f32 v1, v14, v15
	v_lshlrev_b32_e32 v14, 16, v13
	v_and_b32_e32 v15, 0xffff0000, v13
	v_mul_f32_e32 v13, 0xbfb8aa3b, v14
	v_exp_f32_e32 v16, v13
	v_mul_f32_e32 v13, 0xbfb8aa3b, v15
	v_exp_f32_e32 v17, v13
	v_rcp_f32_e32 v34, v38
	v_rcp_f32_e32 v35, v39
	v_lshlrev_b32_e32 v12, 16, v2
	v_and_b32_e32 v13, 0xffff0000, v2
	v_add_f32_e32 v2, 1.0, v16
	v_rcp_f32_e32 v16, v2
	v_add_f32_e32 v2, 1.0, v17
	v_rcp_f32_e32 v17, v2
	v_cvt_pk_bf16_f32 v0, v10, v11
	v_pk_mul_f32 v[10:11], v[34:35], v[28:29]
	s_nop 0
	v_pk_mul_f32 v[10:11], v[10:11], v[12:13]
	v_lshlrev_b32_e32 v12, 16, v3
	s_nop 0
	v_pk_mul_f32 v[10:11], v[18:19], v[10:11]
	v_and_b32_e32 v13, 0xffff0000, v3
	v_cvt_pk_bf16_f32 v2, v10, v11
	v_pk_mul_f32 v[10:11], v[16:17], v[14:15]
	s_nop 0
	v_pk_mul_f32 v[10:11], v[10:11], v[12:13]
	s_nop 0
	v_pk_mul_f32 v[10:11], v[20:21], v[10:11]
	s_nop 0
	v_cvt_pk_bf16_f32 v3, v10, v11
	v_lshl_add_u64 v[10:11], v[4:5], 0, v[22:23]
	global_store_dwordx4 v[10:11], v[0:3], off
	s_nop 1
	v_mov_b32_e32 v1, s25
	v_or_b32_e32 v0, s24, v118
	v_lshlrev_b64 v[26:27], 11, v[0:1]
	v_lshl_add_u64 v[0:1], v[8:9], 0, v[26:27]
	s_nop 1
	s_waitcnt vmcnt(7)
	v_mov_b32_e32 v10, v148
	v_mov_b32_e32 v11, v149
	v_mov_b32_e32 v12, v150
	v_mov_b32_e32 v13, v151
	v_mov_b32_e32 v14, v164
	v_mov_b32_e32 v15, v165
	v_mov_b32_e32 v16, v166
	v_mov_b32_e32 v17, v167
	v_mov_b32_e32 v18, v168
	v_mov_b32_e32 v19, v169
	v_mov_b32_e32 v20, v170
	v_mov_b32_e32 v21, v171
	ds_read_b128 v[22:25], v129 offset:45312
	ds_read_b128 v[0:3], v129 offset:46400
	s_waitcnt lgkmcnt(1)
; #define LAS __attribute__((address_space(3)))
; __device__ __forceinline__ unsigned pk2(float lo, float hi) { return cvt_pk_bf16(lo, hi); }
; __device__ __forceinline__ float fsigmoid(float x) { return __builtin_amdgcn_rcpf(1.0f + fexp(-x)); }
; __device__ __forceinline__ void phase_ret_out(const Frame& F, const Args& a, int l) {
;     ...
;         for (int j = 0; j < 8; ++j) {
;             const int idx = lane + 64 * j, q = idx >> 4, cv = idx & 15, col = h * 256 + 128 * dj + 8 * cv;
;             const v4u ov = *(const LAS v4u*)(stg + q * PLD + cv * 16);
;             const size_t tok = tok0 + 32 * qi + q;
;             const v4u gv = *(const v4u*)(RG + tok * 1024 + col);
;             const f32x4 r0 = *(const f32x4*)(rn + col), r1 = *(const f32x4*)(rn + col + 4);
;             const float rr[8] = {r0.x, r0.y, r0.z, r0.w, r1.x, r1.y, r1.z, r1.w};
;             v4u wv;
; #pragma unroll
;             for (int q2 = 0; q2 < 4; ++q2) { const float ga = bf_lo(gv[q2]), gb = bf_hi(gv[q2]);
;                 wv[q2] = pk2(ga * fsigmoid(ga) * bf_lo(ov[q2]) * rr[2 * q2], gb * fsigmoid(gb) * bf_hi(ov[q2]) * rr[2 * q2 + 1]); }
;             *(v4u*)(YB + tok * 1024 + col) = wv;
	v_lshlrev_b32_e32 v28, 16, v22
	v_and_b32_e32 v29, 0xffff0000, v22
	v_lshlrev_b32_e32 v22, 16, v23
	v_and_b32_e32 v23, 0xffff0000, v23
	v_lshlrev_b32_e32 v30, 16, v24
	v_and_b32_e32 v31, 0xffff0000, v24
	v_lshlrev_b32_e32 v24, 16, v25
	v_and_b32_e32 v25, 0xffff0000, v25
	s_nop 0
	v_lshlrev_b32_e32 v32, 16, v10
	v_and_b32_e32 v33, 0xffff0000, v10
	v_lshlrev_b32_e32 v10, 16, v11
	v_and_b32_e32 v11, 0xffff0000, v11
	v_lshlrev_b32_e32 v34, 16, v12
	v_and_b32_e32 v35, 0xffff0000, v12
	v_lshlrev_b32_e32 v12, 16, v13
	v_and_b32_e32 v13, 0xffff0000, v13
	v_mul_f32_e32 v36, 0xbfb8aa3b, v32
	v_mul_f32_e32 v37, 0xbfb8aa3b, v33
	v_mul_f32_e32 v38, 0xbfb8aa3b, v10
	v_mul_f32_e32 v39, 0xbfb8aa3b, v11
	v_mul_f32_e32 v40, 0xbfb8aa3b, v34
	v_mul_f32_e32 v41, 0xbfb8aa3b, v35
	v_mul_f32_e32 v42, 0xbfb8aa3b, v12
	v_mul_f32_e32 v43, 0xbfb8aa3b, v13
	v_exp_f32_e32 v36, v36
	v_exp_f32_e32 v37, v37
	v_exp_f32_e32 v38, v38
	v_exp_f32_e32 v39, v39
	v_exp_f32_e32 v40, v40
	v_exp_f32_e32 v41, v41
	v_exp_f32_e32 v42, v42
	v_exp_f32_e32 v43, v43
	v_add_f32_e32 v36, 1.0, v36
	v_add_f32_e32 v37, 1.0, v37
	v_add_f32_e32 v38, 1.0, v38
	v_add_f32_e32 v39, 1.0, v39
	v_add_f32_e32 v40, 1.0, v40
	v_add_f32_e32 v41, 1.0, v41
	v_add_f32_e32 v42, 1.0, v42
	v_add_f32_e32 v43, 1.0, v43
	v_rcp_f32_e32 v36, v36
	v_rcp_f32_e32 v37, v37
	v_rcp_f32_e32 v38, v38
	v_rcp_f32_e32 v39, v39
	v_rcp_f32_e32 v40, v40
	v_rcp_f32_e32 v41, v41
	v_rcp_f32_e32 v42, v42
	v_rcp_f32_e32 v43, v43
	v_pk_mul_f32 v[32:33], v[36:37], v[32:33]
	v_pk_mul_f32 v[10:11], v[38:39], v[10:11]
	v_pk_mul_f32 v[34:35], v[40:41], v[34:35]
	v_pk_mul_f32 v[12:13], v[42:43], v[12:13]
	v_pk_mul_f32 v[28:29], v[32:33], v[28:29]
	v_pk_mul_f32 v[10:11], v[10:11], v[22:23]
	v_pk_mul_f32 v[22:23], v[34:35], v[30:31]
	v_pk_mul_f32 v[24:25], v[12:13], v[24:25]
	s_nop 0
	v_pk_mul_f32 v[12:13], v[14:15], v[28:29]
	v_pk_mul_f32 v[14:15], v[16:17], v[10:11]
	s_nop 0
	v_pk_mul_f32 v[16:17], v[18:19], v[22:23]
	v_cvt_pk_bf16_f32 v11, v14, v15
	v_pk_mul_f32 v[14:15], v[20:21], v[24:25]
	v_cvt_pk_bf16_f32 v10, v12, v13
	v_cvt_pk_bf16_f32 v12, v16, v17
	v_cvt_pk_bf16_f32 v13, v14, v15
	v_lshl_add_u64 v[14:15], v[4:5], 0, v[26:27]
	global_store_dwordx4 v[14:15], v[10:13], off
	s_waitcnt lgkmcnt(0)
	v_lshlrev_b32_e32 v28, 16, v0
	v_and_b32_e32 v29, 0xffff0000, v0
	v_mov_b32_e32 v11, s25
	v_or_b32_e32 v10, s24, v120
	v_lshlrev_b64 v[22:23], 11, v[10:11]
	v_lshl_add_u64 v[10:11], v[8:9], 0, v[22:23]
	s_nop 1
	s_waitcnt vmcnt(7)
	v_mov_b32_e32 v10, v152
	v_mov_b32_e32 v11, v153
	v_mov_b32_e32 v12, v154
	v_mov_b32_e32 v13, v155
	s_nop 0
	v_mov_b32_e32 v14, v164
	v_mov_b32_e32 v15, v165
	v_mov_b32_e32 v16, v166
	v_mov_b32_e32 v17, v167
	v_mov_b32_e32 v18, v168
	v_mov_b32_e32 v19, v169
	v_mov_b32_e32 v20, v170
	v_mov_b32_e32 v21, v171
	v_lshlrev_b32_e32 v0, 16, v1
	v_and_b32_e32 v1, 0xffff0000, v1
	v_lshlrev_b32_e32 v30, 16, v2
	v_and_b32_e32 v31, 0xffff0000, v2
	v_lshlrev_b32_e32 v2, 16, v3
	v_and_b32_e32 v3, 0xffff0000, v3
	v_mov_b32_e32 v25, s25
	v_or_b32_e32 v24, s24, v122
	v_lshlrev_b64 v[24:25], 11, v[24:25]
	v_lshl_add_u64 v[22:23], v[4:5], 0, v[22:23]
	v_lshl_add_u64 v[26:27], v[8:9], 0, v[24:25]
	s_nop 0
	v_lshlrev_b32_e32 v32, 16, v10
	v_and_b32_e32 v33, 0xffff0000, v10
	v_lshlrev_b32_e32 v10, 16, v11
	v_and_b32_e32 v11, 0xffff0000, v11
	v_lshlrev_b32_e32 v34, 16, v12
	v_and_b32_e32 v35, 0xffff0000, v12
	v_lshlrev_b32_e32 v12, 16, v13
	v_and_b32_e32 v13, 0xffff0000, v13
	v_mul_f32_e32 v36, 0xbfb8aa3b, v32
	v_mul_f32_e32 v37, 0xbfb8aa3b, v33
	v_mul_f32_e32 v38, 0xbfb8aa3b, v10
	v_mul_f32_e32 v39, 0xbfb8aa3b, v11
	v_mul_f32_e32 v40, 0xbfb8aa3b, v34
	v_mul_f32_e32 v41, 0xbfb8aa3b, v35
	v_mul_f32_e32 v42, 0xbfb8aa3b, v12
	v_mul_f32_e32 v43, 0xbfb8aa3b, v13
	v_exp_f32_e32 v36, v36
	v_exp_f32_e32 v37, v37
	v_exp_f32_e32 v38, v38
	v_exp_f32_e32 v39, v39
	v_exp_f32_e32 v40, v40
	v_exp_f32_e32 v41, v41
	v_exp_f32_e32 v42, v42
	v_exp_f32_e32 v43, v43
	v_add_f32_e32 v36, 1.0, v36
	v_add_f32_e32 v37, 1.0, v37
	v_add_f32_e32 v38, 1.0, v38
	v_add_f32_e32 v39, 1.0, v39
	v_add_f32_e32 v40, 1.0, v40
	v_add_f32_e32 v41, 1.0, v41
	v_add_f32_e32 v42, 1.0, v42
	v_add_f32_e32 v43, 1.0, v43
	v_rcp_f32_e32 v36, v36
	v_rcp_f32_e32 v37, v37
	v_rcp_f32_e32 v38, v38
	v_rcp_f32_e32 v39, v39
	v_rcp_f32_e32 v40, v40
	v_rcp_f32_e32 v41, v41
	v_rcp_f32_e32 v42, v42
	v_rcp_f32_e32 v43, v43
	v_pk_mul_f32 v[32:33], v[36:37], v[32:33]
	v_pk_mul_f32 v[10:11], v[38:39], v[10:11]
	v_pk_mul_f32 v[34:35], v[40:41], v[34:35]
	v_pk_mul_f32 v[12:13], v[42:43], v[12:13]
	v_pk_mul_f32 v[28:29], v[32:33], v[28:29]
	v_pk_mul_f32 v[0:1], v[10:11], v[0:1]
	v_pk_mul_f32 v[10:11], v[34:35], v[30:31]
	v_pk_mul_f32 v[2:3], v[12:13], v[2:3]
	s_nop 0
	v_pk_mul_f32 v[12:13], v[14:15], v[28:29]
	v_pk_mul_f32 v[14:15], v[16:17], v[0:1]
	s_nop 0
	v_pk_mul_f32 v[10:11], v[18:19], v[10:11]
	v_pk_mul_f32 v[16:17], v[20:21], v[2:3]
	v_cvt_pk_bf16_f32 v0, v12, v13
	v_cvt_pk_bf16_f32 v1, v14, v15
	v_cvt_pk_bf16_f32 v2, v10, v11
	v_cvt_pk_bf16_f32 v3, v16, v17
	global_store_dwordx4 v[22:23], v[0:3], off
	s_nop 1
	s_waitcnt vmcnt(7)
; #define LAS __attribute__((address_space(3)))
; __device__ __forceinline__ unsigned pk2(float lo, float hi) { return cvt_pk_bf16(lo, hi); }
; __device__ __forceinline__ float fsigmoid(float x) { return __builtin_amdgcn_rcpf(1.0f + fexp(-x)); }
; __device__ __forceinline__ void phase_ret_out(const Frame& F, const Args& a, int l) {
;     ...
;         for (int j = 0; j < 8; ++j) {
;             const int idx = lane + 64 * j, q = idx >> 4, cv = idx & 15, col = h * 256 + 128 * dj + 8 * cv;
;             const v4u ov = *(const LAS v4u*)(stg + q * PLD + cv * 16);
;             const size_t tok = tok0 + 32 * qi + q;
;             const v4u gv = *(const v4u*)(RG + tok * 1024 + col);
;             const f32x4 r0 = *(const f32x4*)(rn + col), r1 = *(const f32x4*)(rn + col + 4);
;             const float rr[8] = {r0.x, r0.y, r0.z, r0.w, r1.x, r1.y, r1.z, r1.w};
;             v4u wv;
; #pragma unroll
;             for (int q2 = 0; q2 < 4; ++q2) { const float ga = bf_lo(gv[q2]), gb = bf_hi(gv[q2]);
;                 wv[q2] = pk2(ga * fsigmoid(ga) * bf_lo(ov[q2]) * rr[2 * q2], gb * fsigmoid(gb) * bf_hi(ov[q2]) * rr[2 * q2 + 1]); }
;             *(v4u*)(YB + tok * 1024 + col) = wv;
	v_mov_b32_e32 v0, v156
	v_mov_b32_e32 v1, v157
	v_mov_b32_e32 v2, v158
	v_mov_b32_e32 v3, v159
	s_nop 0
	v_mov_b32_e32 v10, v164
	v_mov_b32_e32 v11, v165
	v_mov_b32_e32 v12, v166
	v_mov_b32_e32 v13, v167
	v_mov_b32_e32 v14, v168
	v_mov_b32_e32 v15, v169
	v_mov_b32_e32 v16, v170
	v_mov_b32_e32 v17, v171
	ds_read_b128 v[18:21], v129 offset:47488
	v_mov_b32_e32 v23, s25
	v_or_b32_e32 v22, s24, v124
	v_lshlrev_b64 v[26:27], 11, v[22:23]
	v_lshl_add_u64 v[28:29], v[4:5], 0, v[24:25]
	ds_read_b128 v[22:25], v129 offset:48576
	s_waitcnt lgkmcnt(1)
	v_lshlrev_b32_e32 v30, 16, v18
	v_and_b32_e32 v31, 0xffff0000, v18
	v_lshlrev_b32_e32 v18, 16, v19
	v_and_b32_e32 v19, 0xffff0000, v19
	v_lshlrev_b32_e32 v32, 16, v20
	v_and_b32_e32 v33, 0xffff0000, v20
	v_lshlrev_b32_e32 v20, 16, v21
	v_and_b32_e32 v21, 0xffff0000, v21
	v_lshl_add_u64 v[8:9], v[8:9], 0, v[26:27]
	v_lshl_add_u64 v[4:5], v[4:5], 0, v[26:27]
	s_nop 0
	v_lshlrev_b32_e32 v34, 16, v0
	v_and_b32_e32 v35, 0xffff0000, v0
	v_lshlrev_b32_e32 v0, 16, v1
	v_and_b32_e32 v1, 0xffff0000, v1
	v_lshlrev_b32_e32 v36, 16, v2
	v_and_b32_e32 v37, 0xffff0000, v2
	v_lshlrev_b32_e32 v2, 16, v3
	v_and_b32_e32 v3, 0xffff0000, v3
	v_mul_f32_e32 v38, 0xbfb8aa3b, v34
	v_mul_f32_e32 v39, 0xbfb8aa3b, v35
	v_mul_f32_e32 v40, 0xbfb8aa3b, v0
	v_mul_f32_e32 v41, 0xbfb8aa3b, v1
	v_mul_f32_e32 v42, 0xbfb8aa3b, v36
	v_mul_f32_e32 v43, 0xbfb8aa3b, v37
	v_mul_f32_e32 v44, 0xbfb8aa3b, v2
	v_mul_f32_e32 v45, 0xbfb8aa3b, v3
	v_exp_f32_e32 v38, v38
	v_exp_f32_e32 v39, v39
	v_exp_f32_e32 v40, v40
	v_exp_f32_e32 v41, v41
	v_exp_f32_e32 v42, v42
	v_exp_f32_e32 v43, v43
	v_exp_f32_e32 v44, v44
	v_exp_f32_e32 v45, v45
	v_add_f32_e32 v38, 1.0, v38
	v_add_f32_e32 v39, 1.0, v39
	v_add_f32_e32 v40, 1.0, v40
	v_add_f32_e32 v41, 1.0, v41
	v_add_f32_e32 v42, 1.0, v42
	v_add_f32_e32 v43, 1.0, v43
	v_add_f32_e32 v44, 1.0, v44
	v_add_f32_e32 v45, 1.0, v45
	v_rcp_f32_e32 v38, v38
	v_rcp_f32_e32 v39, v39
	v_rcp_f32_e32 v40, v40
	v_rcp_f32_e32 v41, v41
	v_rcp_f32_e32 v42, v42
	v_rcp_f32_e32 v43, v43
	v_rcp_f32_e32 v44, v44
	v_rcp_f32_e32 v45, v45
	v_pk_mul_f32 v[34:35], v[38:39], v[34:35]
	v_pk_mul_f32 v[0:1], v[40:41], v[0:1]
	v_pk_mul_f32 v[36:37], v[42:43], v[36:37]
	v_pk_mul_f32 v[2:3], v[44:45], v[2:3]
	v_pk_mul_f32 v[30:31], v[34:35], v[30:31]
	v_pk_mul_f32 v[0:1], v[0:1], v[18:19]
	v_pk_mul_f32 v[18:19], v[36:37], v[32:33]
	v_pk_mul_f32 v[2:3], v[2:3], v[20:21]
	s_nop 0
	v_pk_mul_f32 v[10:11], v[10:11], v[30:31]
	v_pk_mul_f32 v[12:13], v[12:13], v[0:1]
	s_nop 0
	v_pk_mul_f32 v[14:15], v[14:15], v[18:19]
	v_pk_mul_f32 v[16:17], v[16:17], v[2:3]
	v_cvt_pk_bf16_f32 v0, v10, v11
	v_cvt_pk_bf16_f32 v1, v12, v13
	v_cvt_pk_bf16_f32 v2, v14, v15
	v_cvt_pk_bf16_f32 v3, v16, v17
	global_store_dwordx4 v[28:29], v[0:3], off
	s_nop 1
	s_waitcnt vmcnt(7)
	v_mov_b32_e32 v0, v160
	v_mov_b32_e32 v1, v161
	v_mov_b32_e32 v2, v162
	v_mov_b32_e32 v3, v163
	s_nop 0
	v_mov_b32_e32 v8, v164
	v_mov_b32_e32 v9, v165
	v_mov_b32_e32 v10, v166
	v_mov_b32_e32 v11, v167
	v_mov_b32_e32 v12, v168
	v_mov_b32_e32 v13, v169
	v_mov_b32_e32 v14, v170
	v_mov_b32_e32 v15, v171
	s_waitcnt lgkmcnt(0)
	v_lshlrev_b32_e32 v6, 16, v22
	v_and_b32_e32 v7, 0xffff0000, v22
	v_lshlrev_b32_e32 v16, 16, v23
	v_and_b32_e32 v17, 0xffff0000, v23
	v_lshlrev_b32_e32 v18, 16, v24
	v_and_b32_e32 v19, 0xffff0000, v24
	v_lshlrev_b32_e32 v20, 16, v25
	v_and_b32_e32 v21, 0xffff0000, v25
	s_nop 0
	v_lshlrev_b32_e32 v22, 16, v0
	v_and_b32_e32 v23, 0xffff0000, v0
	v_lshlrev_b32_e32 v0, 16, v1
	v_and_b32_e32 v1, 0xffff0000, v1
	v_lshlrev_b32_e32 v24, 16, v2
	v_and_b32_e32 v25, 0xffff0000, v2
	v_lshlrev_b32_e32 v2, 16, v3
	v_and_b32_e32 v3, 0xffff0000, v3
	v_mul_f32_e32 v26, 0xbfb8aa3b, v22
	v_mul_f32_e32 v27, 0xbfb8aa3b, v23
	v_mul_f32_e32 v28, 0xbfb8aa3b, v0
	v_mul_f32_e32 v29, 0xbfb8aa3b, v1
	v_mul_f32_e32 v30, 0xbfb8aa3b, v24
	v_mul_f32_e32 v31, 0xbfb8aa3b, v25
	v_mul_f32_e32 v32, 0xbfb8aa3b, v2
	v_mul_f32_e32 v33, 0xbfb8aa3b, v3
	v_exp_f32_e32 v26, v26
	v_exp_f32_e32 v27, v27
	v_exp_f32_e32 v28, v28
	v_exp_f32_e32 v29, v29
	v_exp_f32_e32 v30, v30
	v_exp_f32_e32 v31, v31
	v_exp_f32_e32 v32, v32
	v_exp_f32_e32 v33, v33
	v_add_f32_e32 v26, 1.0, v26
	v_add_f32_e32 v27, 1.0, v27
	v_add_f32_e32 v28, 1.0, v28
	v_add_f32_e32 v29, 1.0, v29
	v_add_f32_e32 v30, 1.0, v30
	v_add_f32_e32 v31, 1.0, v31
	v_add_f32_e32 v32, 1.0, v32
	v_add_f32_e32 v33, 1.0, v33
	v_rcp_f32_e32 v26, v26
	v_rcp_f32_e32 v27, v27
	v_rcp_f32_e32 v28, v28
	v_rcp_f32_e32 v29, v29
	v_rcp_f32_e32 v30, v30
	v_rcp_f32_e32 v31, v31
	v_rcp_f32_e32 v32, v32
	v_rcp_f32_e32 v33, v33
	v_pk_mul_f32 v[22:23], v[26:27], v[22:23]
	v_pk_mul_f32 v[0:1], v[28:29], v[0:1]
	v_pk_mul_f32 v[24:25], v[30:31], v[24:25]
	v_pk_mul_f32 v[2:3], v[32:33], v[2:3]
	v_pk_mul_f32 v[6:7], v[22:23], v[6:7]
	v_pk_mul_f32 v[0:1], v[0:1], v[16:17]
	v_pk_mul_f32 v[16:17], v[24:25], v[18:19]
	v_pk_mul_f32 v[2:3], v[2:3], v[20:21]
	s_nop 0
	v_pk_mul_f32 v[6:7], v[8:9], v[6:7]
	v_pk_mul_f32 v[8:9], v[10:11], v[0:1]
	s_nop 0
	v_pk_mul_f32 v[10:11], v[12:13], v[16:17]
	v_pk_mul_f32 v[12:13], v[14:15], v[2:3]
	v_cvt_pk_bf16_f32 v0, v6, v7
	v_cvt_pk_bf16_f32 v1, v8, v9
	v_cvt_pk_bf16_f32 v2, v10, v11
	v_cvt_pk_bf16_f32 v3, v12, v13
	global_store_dwordx4 v[4:5], v[0:3], off
	s_cbranch_scc0 .LBB0_1210
